# bf16-residual GEMM epilogue (GEMM4, GEMM2 layer 1) rewritten: batched rs2 loads, x loads one row ahead of the stores, counted vmcnt
# baseline (speedup 1.0000x reference)
; __device__ __forceinline__ float fx_get(const long long* p, float inv) { return (float)(*(const GAS long long*)p) * inv; }
;     template <bool XF32> __device__ __forceinline__ void store_res(const f32x4 (&acc)[2][2][4][2], const pg8::Unit& u, int wr, int wc, int fr, int fq) const {
;     ...
;         for (int ai = 0; ai < 2; ++ai) {
;             float rsc[4];
; #pragma unroll
;             for (int m = 0; m < 4; ++m) rsc[m] = rs2 ? __builtin_amdgcn_rsqf(fx_get(rs2 + SEQ + row0 + ai * 128 + m * 16, FX_RS_INV) * (1.0f / 1024.0f) + RMS_EPS) : 1.0f;
.LBB0_452:
	v_mov_b64_e32 v[250:251], v[132:133]
	v_mov_b32_e32 v132, 1.0
	v_mov_b32_e32 v133, 1.0
	v_mov_b32_e32 v134, 1.0
	v_mov_b32_e32 v135, 1.0
	v_mov_b32_e32 v136, 1.0
	v_mov_b32_e32 v137, 1.0
	v_mov_b32_e32 v138, 1.0
	v_mov_b32_e32 v139, 1.0
	s_and_b64 vcc, exec, s[4:5]
	s_cbranch_vccnz .Lmy_bf_nors
	global_load_dwordx2 v[230:231], v[250:251], off
	global_load_dwordx2 v[232:233], v[250:251], off offset:128
	global_load_dwordx2 v[234:235], v[250:251], off offset:256
	global_load_dwordx2 v[236:237], v[250:251], off offset:384
	global_load_dwordx2 v[238:239], v[250:251], off offset:1024
	global_load_dwordx2 v[240:241], v[250:251], off offset:1152
	global_load_dwordx2 v[242:243], v[250:251], off offset:1280
	global_load_dwordx2 v[244:245], v[250:251], off offset:1408
	s_waitcnt vmcnt(0)
	v_xor_b32_e32 v142, v230, v231
	v_ffbh_i32_e32 v143, v231
	v_ashrrev_i32_e32 v142, 31, v142
	v_add_u32_e32 v143, -1, v143
	v_add_u32_e32 v142, 32, v142
	v_min_u32_e32 v143, v143, v142
	v_lshlrev_b64 v[230:231], v143, v[230:231]
	v_min_u32_e32 v230, 1, v230
	v_or_b32_e32 v230, v231, v230
	v_cvt_f32_i32_e32 v230, v230
	v_sub_u32_e32 v143, 32, v143
	v_ldexp_f32 v143, v230, v143
	v_mul_f32_e32 v143, 0x33800000, v143
	v_fmamk_f32 v143, v143, 0x3a800000, v223
	v_rsq_f32_e32 v132, v143
	v_xor_b32_e32 v144, v232, v233
	v_ffbh_i32_e32 v145, v233
	v_ashrrev_i32_e32 v144, 31, v144
	v_add_u32_e32 v145, -1, v145
	v_add_u32_e32 v144, 32, v144
	v_min_u32_e32 v145, v145, v144
	v_lshlrev_b64 v[232:233], v145, v[232:233]
	v_min_u32_e32 v232, 1, v232
	v_or_b32_e32 v232, v233, v232
	v_cvt_f32_i32_e32 v232, v232
	v_sub_u32_e32 v145, 32, v145
	v_ldexp_f32 v145, v232, v145
	v_mul_f32_e32 v145, 0x33800000, v145
	v_fmamk_f32 v145, v145, 0x3a800000, v223
	v_rsq_f32_e32 v133, v145
	v_xor_b32_e32 v142, v234, v235
	v_ffbh_i32_e32 v143, v235
	v_ashrrev_i32_e32 v142, 31, v142
	v_add_u32_e32 v143, -1, v143
	v_add_u32_e32 v142, 32, v142
	v_min_u32_e32 v143, v143, v142
	v_lshlrev_b64 v[234:235], v143, v[234:235]
	v_min_u32_e32 v234, 1, v234
	v_or_b32_e32 v234, v235, v234
	v_cvt_f32_i32_e32 v234, v234
	v_sub_u32_e32 v143, 32, v143
	v_ldexp_f32 v143, v234, v143
	v_mul_f32_e32 v143, 0x33800000, v143
	v_fmamk_f32 v143, v143, 0x3a800000, v223
	v_rsq_f32_e32 v134, v143
	v_xor_b32_e32 v144, v236, v237
	v_ffbh_i32_e32 v145, v237
	v_ashrrev_i32_e32 v144, 31, v144
	v_add_u32_e32 v145, -1, v145
	v_add_u32_e32 v144, 32, v144
	v_min_u32_e32 v145, v145, v144
	v_lshlrev_b64 v[236:237], v145, v[236:237]
	v_min_u32_e32 v236, 1, v236
	v_or_b32_e32 v236, v237, v236
	v_cvt_f32_i32_e32 v236, v236
	v_sub_u32_e32 v145, 32, v145
	v_ldexp_f32 v145, v236, v145
	v_mul_f32_e32 v145, 0x33800000, v145
	v_fmamk_f32 v145, v145, 0x3a800000, v223
	v_rsq_f32_e32 v135, v145
	v_xor_b32_e32 v142, v238, v239
	v_ffbh_i32_e32 v143, v239
	v_ashrrev_i32_e32 v142, 31, v142
	v_add_u32_e32 v143, -1, v143
	v_add_u32_e32 v142, 32, v142
	v_min_u32_e32 v143, v143, v142
	v_lshlrev_b64 v[238:239], v143, v[238:239]
	v_min_u32_e32 v238, 1, v238
	v_or_b32_e32 v238, v239, v238
	v_cvt_f32_i32_e32 v238, v238
	v_sub_u32_e32 v143, 32, v143
	v_ldexp_f32 v143, v238, v143
	v_mul_f32_e32 v143, 0x33800000, v143
	v_fmamk_f32 v143, v143, 0x3a800000, v223
	v_rsq_f32_e32 v136, v143
	v_xor_b32_e32 v144, v240, v241
	v_ffbh_i32_e32 v145, v241
	v_ashrrev_i32_e32 v144, 31, v144
	v_add_u32_e32 v145, -1, v145
	v_add_u32_e32 v144, 32, v144
	v_min_u32_e32 v145, v145, v144
	v_lshlrev_b64 v[240:241], v145, v[240:241]
	v_min_u32_e32 v240, 1, v240
	v_or_b32_e32 v240, v241, v240
	v_cvt_f32_i32_e32 v240, v240
	v_sub_u32_e32 v145, 32, v145
	v_ldexp_f32 v145, v240, v145
	v_mul_f32_e32 v145, 0x33800000, v145
	v_fmamk_f32 v145, v145, 0x3a800000, v223
	v_rsq_f32_e32 v137, v145
	v_xor_b32_e32 v142, v242, v243
	v_ffbh_i32_e32 v143, v243
	v_ashrrev_i32_e32 v142, 31, v142
	v_add_u32_e32 v143, -1, v143
	v_add_u32_e32 v142, 32, v142
	v_min_u32_e32 v143, v143, v142
	v_lshlrev_b64 v[242:243], v143, v[242:243]
	v_min_u32_e32 v242, 1, v242
	v_or_b32_e32 v242, v243, v242
	v_cvt_f32_i32_e32 v242, v242
	v_sub_u32_e32 v143, 32, v143
	v_ldexp_f32 v143, v242, v143
	v_mul_f32_e32 v143, 0x33800000, v143
	v_fmamk_f32 v143, v143, 0x3a800000, v223
	v_rsq_f32_e32 v138, v143
	v_xor_b32_e32 v144, v244, v245
	v_ffbh_i32_e32 v145, v245
	v_ashrrev_i32_e32 v144, 31, v144
	v_add_u32_e32 v145, -1, v145
	v_add_u32_e32 v144, 32, v144
	v_min_u32_e32 v145, v145, v144
	v_lshlrev_b64 v[244:245], v145, v[244:245]
	v_min_u32_e32 v244, 1, v244
	v_or_b32_e32 v244, v245, v244
	v_cvt_f32_i32_e32 v244, v244
	v_sub_u32_e32 v145, 32, v145
	v_ldexp_f32 v145, v244, v145
	v_mul_f32_e32 v145, 0x33800000, v145
	v_fmamk_f32 v145, v145, 0x3a800000, v223
	v_rsq_f32_e32 v139, v145
; #define GAS __attribute__((address_space(1)))
; __device__ __forceinline__ unsigned cvt_pk_bf16(float lo, float hi) { const f32x2 v = {lo, hi}; const bf16x2_t b = __builtin_convertvector(v, bf16x2_t); return __builtin_bit_cast(unsigned, b); }
; __device__ __forceinline__ float fx_get(const long long* p, float inv) { return (float)(*(const GAS long long*)p) * inv; }
;     template <bool XF32> __device__ __forceinline__ void store_res(const f32x4 (&acc)[2][2][4][2], const pg8::Unit& u, int wr, int wc, int fr, int fq) const {
;     ...
;             for (int m = 0; m < 4; ++m) rsc[m] = rs2 ? __builtin_amdgcn_rsqf(fx_get(rs2 + SEQ + row0 + ai * 128 + m * 16, FX_RS_INV) * (1.0f / 1024.0f) + RMS_EPS) : 1.0f;
;             u32x4 xpre[4][2];
;             if (!XF32) {
; #pragma unroll
;                 for (int m = 0; m < 4; ++m)
; #pragma unroll
;                     for (int bj = 0; bj < 2; ++bj) xpre[m][bj] = *(const GAS u32x4*)(O + (size_t)(row0 + ai * 128 + m * 16) * DM + col0 + bj * 128); }
; #pragma unroll
;             for (int m = 0; m < 4; ++m) { const size_t off = (size_t)(row0 + ai * 128 + m * 16) * DM + col0;
; #pragma unroll
;                 for (int bj = 0; bj < 2; ++bj) { f32x4 x0, x1;
;                     if (XF32) { x0 = *(const GAS f32x4*)(xin + off + bj * 128); x1 = *(const GAS f32x4*)(xin + off + bj * 128 + 4); }
;                     else { const u32x4 xb = xpre[m][bj];
;                         x0 = (f32x4){bf2f((unsigned short)(xb.x & 0xffff)), bf2f((unsigned short)(xb.x >> 16)), bf2f((unsigned short)(xb.y & 0xffff)), bf2f((unsigned short)(xb.y >> 16))};
;                         x1 = (f32x4){bf2f((unsigned short)(xb.z & 0xffff)), bf2f((unsigned short)(xb.z >> 16)), bf2f((unsigned short)(xb.w & 0xffff)), bf2f((unsigned short)(xb.w >> 16))}; }
;                     const f32x4 z0 = ALPHA * x0 + gv[bj][0] * (acc[ai][bj][m][0] * rsc[m]), z1 = ALPHA * x1 + gv[bj][1] * (acc[ai][bj][m][1] * rsc[m]);
;                     u32x4 w; w.x = cvt_pk_bf16(z0[0], z0[1]); w.y = cvt_pk_bf16(z0[2], z0[3]); w.z = cvt_pk_bf16(z1[0], z1[1]); w.w = cvt_pk_bf16(z1[2], z1[3]);
;                     *(GAS u32x4*)(O + off + bj * 128) = w; }
.Lmy_bf_nors:
	v_lshlrev_b64 v[244:245], 11, v[184:185]
	v_lshl_add_u64 v[244:245], v[244:245], 0, v[0:1]
	v_lshl_add_u64 v[202:203], v[244:245], 1, s[10:11]
	v_mov_b64_e32 v[204:205], v[202:203]
	s_mov_b32 s36, 0x10000
	s_mov_b32 s37, 0
	global_load_dwordx4 v[142:145], v[202:203], off
	global_load_dwordx4 v[146:149], v[202:203], off offset:256
	v_lshl_add_u64 v[202:203], v[202:203], 0, s[36:37]
	global_load_dwordx4 v[150:153], v[202:203], off
	global_load_dwordx4 v[210:213], v[202:203], off offset:256
	s_waitcnt vmcnt(2)
	v_lshlrev_b32_e32 v230, 16, v142
	v_and_b32_e32 v231, 0xffff0000, v142
	v_lshlrev_b32_e32 v232, 16, v143
	v_and_b32_e32 v233, 0xffff0000, v143
	v_lshlrev_b32_e32 v234, 16, v144
	v_and_b32_e32 v235, 0xffff0000, v144
	v_lshlrev_b32_e32 v236, 16, v145
	v_and_b32_e32 v237, 0xffff0000, v145
	v_pk_mul_f32 v[140:141], v[128:129], v[132:133] op_sel_hi:[1,0]
	v_pk_mul_f32 v[230:231], v[230:231], s[96:97] op_sel_hi:[1,0]
	v_pk_fma_f32 v[230:231], v[200:201], v[140:141], v[230:231]
	v_pk_mul_f32 v[154:155], v[130:131], v[132:133] op_sel_hi:[1,0]
	v_pk_mul_f32 v[232:233], v[232:233], s[96:97] op_sel_hi:[1,0]
	v_pk_fma_f32 v[232:233], v[198:199], v[154:155], v[232:233]
	v_pk_mul_f32 v[140:141], v[124:125], v[132:133] op_sel_hi:[1,0]
	v_pk_mul_f32 v[234:235], v[234:235], s[96:97] op_sel_hi:[1,0]
	v_pk_fma_f32 v[234:235], v[192:193], v[140:141], v[234:235]
	v_pk_mul_f32 v[154:155], v[126:127], v[132:133] op_sel_hi:[1,0]
	v_pk_mul_f32 v[236:237], v[236:237], s[96:97] op_sel_hi:[1,0]
	v_pk_fma_f32 v[236:237], v[190:191], v[154:155], v[236:237]
	v_cvt_pk_bf16_f32 v238, v230, v231
	v_cvt_pk_bf16_f32 v239, v232, v233
	v_cvt_pk_bf16_f32 v240, v234, v235
	v_cvt_pk_bf16_f32 v241, v236, v237
	global_store_dwordx4 v[204:205], v[238:241], off
	v_lshlrev_b32_e32 v230, 16, v146
	v_and_b32_e32 v231, 0xffff0000, v146
	v_lshlrev_b32_e32 v232, 16, v147
	v_and_b32_e32 v233, 0xffff0000, v147
	v_lshlrev_b32_e32 v234, 16, v148
	v_and_b32_e32 v235, 0xffff0000, v148
	v_lshlrev_b32_e32 v236, 16, v149
	v_and_b32_e32 v237, 0xffff0000, v149
	v_pk_mul_f32 v[140:141], v[120:121], v[132:133] op_sel_hi:[1,0]
	v_pk_mul_f32 v[230:231], v[230:231], s[96:97] op_sel_hi:[1,0]
	v_pk_fma_f32 v[230:231], v[196:197], v[140:141], v[230:231]
	v_pk_mul_f32 v[154:155], v[122:123], v[132:133] op_sel_hi:[1,0]
	v_pk_mul_f32 v[232:233], v[232:233], s[96:97] op_sel_hi:[1,0]
	v_pk_fma_f32 v[232:233], v[194:195], v[154:155], v[232:233]
	v_pk_mul_f32 v[140:141], v[116:117], v[132:133] op_sel_hi:[1,0]
	v_pk_mul_f32 v[234:235], v[234:235], s[96:97] op_sel_hi:[1,0]
	v_pk_fma_f32 v[234:235], v[188:189], v[140:141], v[234:235]
	v_pk_mul_f32 v[154:155], v[118:119], v[132:133] op_sel_hi:[1,0]
	v_pk_mul_f32 v[236:237], v[236:237], s[96:97] op_sel_hi:[1,0]
	v_pk_fma_f32 v[236:237], v[186:187], v[154:155], v[236:237]
	v_cvt_pk_bf16_f32 v242, v230, v231
	v_cvt_pk_bf16_f32 v243, v232, v233
	v_cvt_pk_bf16_f32 v244, v234, v235
	v_cvt_pk_bf16_f32 v245, v236, v237
	global_store_dwordx4 v[204:205], v[242:245], off offset:256
	v_lshl_add_u64 v[204:205], v[204:205], 0, s[36:37]
	v_lshl_add_u64 v[202:203], v[202:203], 0, s[36:37]
	global_load_dwordx4 v[142:145], v[202:203], off
	global_load_dwordx4 v[146:149], v[202:203], off offset:256
	s_waitcnt vmcnt(4)
	v_lshlrev_b32_e32 v230, 16, v150
	v_and_b32_e32 v231, 0xffff0000, v150
	v_lshlrev_b32_e32 v232, 16, v151
	v_and_b32_e32 v233, 0xffff0000, v151
	v_lshlrev_b32_e32 v234, 16, v152
	v_and_b32_e32 v235, 0xffff0000, v152
	v_lshlrev_b32_e32 v236, 16, v153
	v_and_b32_e32 v237, 0xffff0000, v153
	v_pk_mul_f32 v[140:141], v[112:113], v[132:133] op_sel:[0,1]
	v_pk_mul_f32 v[230:231], v[230:231], s[96:97] op_sel_hi:[1,0]
	v_pk_fma_f32 v[230:231], v[200:201], v[140:141], v[230:231]
	v_pk_mul_f32 v[154:155], v[114:115], v[132:133] op_sel:[0,1]
	v_pk_mul_f32 v[232:233], v[232:233], s[96:97] op_sel_hi:[1,0]
	v_pk_fma_f32 v[232:233], v[198:199], v[154:155], v[232:233]
	v_pk_mul_f32 v[140:141], v[108:109], v[132:133] op_sel:[0,1]
	v_pk_mul_f32 v[234:235], v[234:235], s[96:97] op_sel_hi:[1,0]
	v_pk_fma_f32 v[234:235], v[192:193], v[140:141], v[234:235]
	v_pk_mul_f32 v[154:155], v[110:111], v[132:133] op_sel:[0,1]
	v_pk_mul_f32 v[236:237], v[236:237], s[96:97] op_sel_hi:[1,0]
	v_pk_fma_f32 v[236:237], v[190:191], v[154:155], v[236:237]
	v_cvt_pk_bf16_f32 v238, v230, v231
	v_cvt_pk_bf16_f32 v239, v232, v233
	v_cvt_pk_bf16_f32 v240, v234, v235
	v_cvt_pk_bf16_f32 v241, v236, v237
	global_store_dwordx4 v[204:205], v[238:241], off
	v_lshlrev_b32_e32 v230, 16, v210
	v_and_b32_e32 v231, 0xffff0000, v210
	v_lshlrev_b32_e32 v232, 16, v211
	v_and_b32_e32 v233, 0xffff0000, v211
	v_lshlrev_b32_e32 v234, 16, v212
	v_and_b32_e32 v235, 0xffff0000, v212
	v_lshlrev_b32_e32 v236, 16, v213
	v_and_b32_e32 v237, 0xffff0000, v213
	v_pk_mul_f32 v[140:141], v[104:105], v[132:133] op_sel:[0,1]
	v_pk_mul_f32 v[230:231], v[230:231], s[96:97] op_sel_hi:[1,0]
	v_pk_fma_f32 v[230:231], v[196:197], v[140:141], v[230:231]
	v_pk_mul_f32 v[154:155], v[106:107], v[132:133] op_sel:[0,1]
	v_pk_mul_f32 v[232:233], v[232:233], s[96:97] op_sel_hi:[1,0]
	v_pk_fma_f32 v[232:233], v[194:195], v[154:155], v[232:233]
	v_pk_mul_f32 v[140:141], v[100:101], v[132:133] op_sel:[0,1]
	v_pk_mul_f32 v[234:235], v[234:235], s[96:97] op_sel_hi:[1,0]
	v_pk_fma_f32 v[234:235], v[188:189], v[140:141], v[234:235]
	v_pk_mul_f32 v[154:155], v[102:103], v[132:133] op_sel:[0,1]
	v_pk_mul_f32 v[236:237], v[236:237], s[96:97] op_sel_hi:[1,0]
	v_pk_fma_f32 v[236:237], v[186:187], v[154:155], v[236:237]
	v_cvt_pk_bf16_f32 v242, v230, v231
	v_cvt_pk_bf16_f32 v243, v232, v233
	v_cvt_pk_bf16_f32 v244, v234, v235
	v_cvt_pk_bf16_f32 v245, v236, v237
	global_store_dwordx4 v[204:205], v[242:245], off offset:256
	v_lshl_add_u64 v[204:205], v[204:205], 0, s[36:37]
	v_lshl_add_u64 v[202:203], v[202:203], 0, s[36:37]
	global_load_dwordx4 v[150:153], v[202:203], off
	global_load_dwordx4 v[210:213], v[202:203], off offset:256
	s_waitcnt vmcnt(4)
; #define GAS __attribute__((address_space(1)))
; __device__ __forceinline__ unsigned cvt_pk_bf16(float lo, float hi) { const f32x2 v = {lo, hi}; const bf16x2_t b = __builtin_convertvector(v, bf16x2_t); return __builtin_bit_cast(unsigned, b); }
;     template <bool XF32> __device__ __forceinline__ void store_res(const f32x4 (&acc)[2][2][4][2], const pg8::Unit& u, int wr, int wc, int fr, int fq) const {
;     ...
;             for (int m = 0; m < 4; ++m) { const size_t off = (size_t)(row0 + ai * 128 + m * 16) * DM + col0;
; #pragma unroll
;                 for (int bj = 0; bj < 2; ++bj) { f32x4 x0, x1;
;                     if (XF32) { x0 = *(const GAS f32x4*)(xin + off + bj * 128); x1 = *(const GAS f32x4*)(xin + off + bj * 128 + 4); }
;                     else { const u32x4 xb = xpre[m][bj];
;                         x0 = (f32x4){bf2f((unsigned short)(xb.x & 0xffff)), bf2f((unsigned short)(xb.x >> 16)), bf2f((unsigned short)(xb.y & 0xffff)), bf2f((unsigned short)(xb.y >> 16))};
;                         x1 = (f32x4){bf2f((unsigned short)(xb.z & 0xffff)), bf2f((unsigned short)(xb.z >> 16)), bf2f((unsigned short)(xb.w & 0xffff)), bf2f((unsigned short)(xb.w >> 16))}; }
;                     const f32x4 z0 = ALPHA * x0 + gv[bj][0] * (acc[ai][bj][m][0] * rsc[m]), z1 = ALPHA * x1 + gv[bj][1] * (acc[ai][bj][m][1] * rsc[m]);
;                     u32x4 w; w.x = cvt_pk_bf16(z0[0], z0[1]); w.y = cvt_pk_bf16(z0[2], z0[3]); w.z = cvt_pk_bf16(z1[0], z1[1]); w.w = cvt_pk_bf16(z1[2], z1[3]);
;                     *(GAS u32x4*)(O + off + bj * 128) = w; }
	v_lshlrev_b32_e32 v230, 16, v142
	v_and_b32_e32 v231, 0xffff0000, v142
	v_lshlrev_b32_e32 v232, 16, v143
	v_and_b32_e32 v233, 0xffff0000, v143
	v_lshlrev_b32_e32 v234, 16, v144
	v_and_b32_e32 v235, 0xffff0000, v144
	v_lshlrev_b32_e32 v236, 16, v145
	v_and_b32_e32 v237, 0xffff0000, v145
	v_pk_mul_f32 v[140:141], v[96:97], v[134:135] op_sel_hi:[1,0]
	v_pk_mul_f32 v[230:231], v[230:231], s[96:97] op_sel_hi:[1,0]
	v_pk_fma_f32 v[230:231], v[200:201], v[140:141], v[230:231]
	v_pk_mul_f32 v[154:155], v[98:99], v[134:135] op_sel_hi:[1,0]
	v_pk_mul_f32 v[232:233], v[232:233], s[96:97] op_sel_hi:[1,0]
	v_pk_fma_f32 v[232:233], v[198:199], v[154:155], v[232:233]
	v_pk_mul_f32 v[140:141], v[92:93], v[134:135] op_sel_hi:[1,0]
	v_pk_mul_f32 v[234:235], v[234:235], s[96:97] op_sel_hi:[1,0]
	v_pk_fma_f32 v[234:235], v[192:193], v[140:141], v[234:235]
	v_pk_mul_f32 v[154:155], v[94:95], v[134:135] op_sel_hi:[1,0]
	v_pk_mul_f32 v[236:237], v[236:237], s[96:97] op_sel_hi:[1,0]
	v_pk_fma_f32 v[236:237], v[190:191], v[154:155], v[236:237]
	v_cvt_pk_bf16_f32 v238, v230, v231
	v_cvt_pk_bf16_f32 v239, v232, v233
	v_cvt_pk_bf16_f32 v240, v234, v235
	v_cvt_pk_bf16_f32 v241, v236, v237
	global_store_dwordx4 v[204:205], v[238:241], off
	v_lshlrev_b32_e32 v230, 16, v146
	v_and_b32_e32 v231, 0xffff0000, v146
	v_lshlrev_b32_e32 v232, 16, v147
	v_and_b32_e32 v233, 0xffff0000, v147
	v_lshlrev_b32_e32 v234, 16, v148
	v_and_b32_e32 v235, 0xffff0000, v148
	v_lshlrev_b32_e32 v236, 16, v149
	v_and_b32_e32 v237, 0xffff0000, v149
	v_pk_mul_f32 v[140:141], v[88:89], v[134:135] op_sel_hi:[1,0]
	v_pk_mul_f32 v[230:231], v[230:231], s[96:97] op_sel_hi:[1,0]
	v_pk_fma_f32 v[230:231], v[196:197], v[140:141], v[230:231]
	v_pk_mul_f32 v[154:155], v[90:91], v[134:135] op_sel_hi:[1,0]
	v_pk_mul_f32 v[232:233], v[232:233], s[96:97] op_sel_hi:[1,0]
	v_pk_fma_f32 v[232:233], v[194:195], v[154:155], v[232:233]
	v_pk_mul_f32 v[140:141], v[84:85], v[134:135] op_sel_hi:[1,0]
	v_pk_mul_f32 v[234:235], v[234:235], s[96:97] op_sel_hi:[1,0]
	v_pk_fma_f32 v[234:235], v[188:189], v[140:141], v[234:235]
	v_pk_mul_f32 v[154:155], v[86:87], v[134:135] op_sel_hi:[1,0]
	v_pk_mul_f32 v[236:237], v[236:237], s[96:97] op_sel_hi:[1,0]
	v_pk_fma_f32 v[236:237], v[186:187], v[154:155], v[236:237]
	v_cvt_pk_bf16_f32 v242, v230, v231
	v_cvt_pk_bf16_f32 v243, v232, v233
	v_cvt_pk_bf16_f32 v244, v234, v235
	v_cvt_pk_bf16_f32 v245, v236, v237
	global_store_dwordx4 v[204:205], v[242:245], off offset:256
	v_lshl_add_u64 v[204:205], v[204:205], 0, s[36:37]
	v_lshl_add_u64 v[202:203], v[202:203], 0, s[36:37]
	v_lshl_add_u64 v[202:203], v[202:203], 0, s[36:37]
	v_lshl_add_u64 v[202:203], v[202:203], 0, s[36:37]
	v_lshl_add_u64 v[202:203], v[202:203], 0, s[36:37]
	v_lshl_add_u64 v[202:203], v[202:203], 0, s[36:37]
	global_load_dwordx4 v[142:145], v[202:203], off
	global_load_dwordx4 v[146:149], v[202:203], off offset:256
	s_waitcnt vmcnt(4)
	v_lshlrev_b32_e32 v230, 16, v150
	v_and_b32_e32 v231, 0xffff0000, v150
	v_lshlrev_b32_e32 v232, 16, v151
	v_and_b32_e32 v233, 0xffff0000, v151
	v_lshlrev_b32_e32 v234, 16, v152
	v_and_b32_e32 v235, 0xffff0000, v152
	v_lshlrev_b32_e32 v236, 16, v153
	v_and_b32_e32 v237, 0xffff0000, v153
	v_pk_mul_f32 v[140:141], v[80:81], v[134:135] op_sel:[0,1]
	v_pk_mul_f32 v[230:231], v[230:231], s[96:97] op_sel_hi:[1,0]
	v_pk_fma_f32 v[230:231], v[200:201], v[140:141], v[230:231]
	v_pk_mul_f32 v[154:155], v[82:83], v[134:135] op_sel:[0,1]
	v_pk_mul_f32 v[232:233], v[232:233], s[96:97] op_sel_hi:[1,0]
	v_pk_fma_f32 v[232:233], v[198:199], v[154:155], v[232:233]
	v_pk_mul_f32 v[140:141], v[76:77], v[134:135] op_sel:[0,1]
	v_pk_mul_f32 v[234:235], v[234:235], s[96:97] op_sel_hi:[1,0]
	v_pk_fma_f32 v[234:235], v[192:193], v[140:141], v[234:235]
	v_pk_mul_f32 v[154:155], v[78:79], v[134:135] op_sel:[0,1]
	v_pk_mul_f32 v[236:237], v[236:237], s[96:97] op_sel_hi:[1,0]
	v_pk_fma_f32 v[236:237], v[190:191], v[154:155], v[236:237]
	v_cvt_pk_bf16_f32 v238, v230, v231
	v_cvt_pk_bf16_f32 v239, v232, v233
	v_cvt_pk_bf16_f32 v240, v234, v235
	v_cvt_pk_bf16_f32 v241, v236, v237
	global_store_dwordx4 v[204:205], v[238:241], off
	v_lshlrev_b32_e32 v230, 16, v210
	v_and_b32_e32 v231, 0xffff0000, v210
	v_lshlrev_b32_e32 v232, 16, v211
	v_and_b32_e32 v233, 0xffff0000, v211
	v_lshlrev_b32_e32 v234, 16, v212
	v_and_b32_e32 v235, 0xffff0000, v212
	v_lshlrev_b32_e32 v236, 16, v213
	v_and_b32_e32 v237, 0xffff0000, v213
	v_pk_mul_f32 v[140:141], v[72:73], v[134:135] op_sel:[0,1]
	v_pk_mul_f32 v[230:231], v[230:231], s[96:97] op_sel_hi:[1,0]
	v_pk_fma_f32 v[230:231], v[196:197], v[140:141], v[230:231]
	v_pk_mul_f32 v[154:155], v[74:75], v[134:135] op_sel:[0,1]
	v_pk_mul_f32 v[232:233], v[232:233], s[96:97] op_sel_hi:[1,0]
	v_pk_fma_f32 v[232:233], v[194:195], v[154:155], v[232:233]
	v_pk_mul_f32 v[140:141], v[68:69], v[134:135] op_sel:[0,1]
	v_pk_mul_f32 v[234:235], v[234:235], s[96:97] op_sel_hi:[1,0]
	v_pk_fma_f32 v[234:235], v[188:189], v[140:141], v[234:235]
	v_pk_mul_f32 v[154:155], v[70:71], v[134:135] op_sel:[0,1]
	v_pk_mul_f32 v[236:237], v[236:237], s[96:97] op_sel_hi:[1,0]
	v_pk_fma_f32 v[236:237], v[186:187], v[154:155], v[236:237]
	v_cvt_pk_bf16_f32 v242, v230, v231
	v_cvt_pk_bf16_f32 v243, v232, v233
	v_cvt_pk_bf16_f32 v244, v234, v235
	v_cvt_pk_bf16_f32 v245, v236, v237
	global_store_dwordx4 v[204:205], v[242:245], off offset:256
	v_lshl_add_u64 v[204:205], v[204:205], 0, s[36:37]
	v_lshl_add_u64 v[204:205], v[204:205], 0, s[36:37]
	v_lshl_add_u64 v[204:205], v[204:205], 0, s[36:37]
	v_lshl_add_u64 v[204:205], v[204:205], 0, s[36:37]
	v_lshl_add_u64 v[204:205], v[204:205], 0, s[36:37]
	v_lshl_add_u64 v[202:203], v[202:203], 0, s[36:37]
	global_load_dwordx4 v[150:153], v[202:203], off
	global_load_dwordx4 v[210:213], v[202:203], off offset:256
	s_waitcnt vmcnt(4)
; #define GAS __attribute__((address_space(1)))
; __device__ __forceinline__ unsigned cvt_pk_bf16(float lo, float hi) { const f32x2 v = {lo, hi}; const bf16x2_t b = __builtin_convertvector(v, bf16x2_t); return __builtin_bit_cast(unsigned, b); }
;     template <bool XF32> __device__ __forceinline__ void store_res(const f32x4 (&acc)[2][2][4][2], const pg8::Unit& u, int wr, int wc, int fr, int fq) const {
;     ...
;             for (int m = 0; m < 4; ++m) { const size_t off = (size_t)(row0 + ai * 128 + m * 16) * DM + col0;
; #pragma unroll
;                 for (int bj = 0; bj < 2; ++bj) { f32x4 x0, x1;
;                     if (XF32) { x0 = *(const GAS f32x4*)(xin + off + bj * 128); x1 = *(const GAS f32x4*)(xin + off + bj * 128 + 4); }
;                     else { const u32x4 xb = xpre[m][bj];
;                         x0 = (f32x4){bf2f((unsigned short)(xb.x & 0xffff)), bf2f((unsigned short)(xb.x >> 16)), bf2f((unsigned short)(xb.y & 0xffff)), bf2f((unsigned short)(xb.y >> 16))};
;                         x1 = (f32x4){bf2f((unsigned short)(xb.z & 0xffff)), bf2f((unsigned short)(xb.z >> 16)), bf2f((unsigned short)(xb.w & 0xffff)), bf2f((unsigned short)(xb.w >> 16))}; }
;                     const f32x4 z0 = ALPHA * x0 + gv[bj][0] * (acc[ai][bj][m][0] * rsc[m]), z1 = ALPHA * x1 + gv[bj][1] * (acc[ai][bj][m][1] * rsc[m]);
;                     u32x4 w; w.x = cvt_pk_bf16(z0[0], z0[1]); w.y = cvt_pk_bf16(z0[2], z0[3]); w.z = cvt_pk_bf16(z1[0], z1[1]); w.w = cvt_pk_bf16(z1[2], z1[3]);
;                     *(GAS u32x4*)(O + off + bj * 128) = w; }
	v_lshlrev_b32_e32 v230, 16, v142
	v_and_b32_e32 v231, 0xffff0000, v142
	v_lshlrev_b32_e32 v232, 16, v143
	v_and_b32_e32 v233, 0xffff0000, v143
	v_lshlrev_b32_e32 v234, 16, v144
	v_and_b32_e32 v235, 0xffff0000, v144
	v_lshlrev_b32_e32 v236, 16, v145
	v_and_b32_e32 v237, 0xffff0000, v145
	v_pk_mul_f32 v[140:141], v[64:65], v[136:137] op_sel_hi:[1,0]
	v_pk_mul_f32 v[230:231], v[230:231], s[96:97] op_sel_hi:[1,0]
	v_pk_fma_f32 v[230:231], v[200:201], v[140:141], v[230:231]
	v_pk_mul_f32 v[154:155], v[66:67], v[136:137] op_sel_hi:[1,0]
	v_pk_mul_f32 v[232:233], v[232:233], s[96:97] op_sel_hi:[1,0]
	v_pk_fma_f32 v[232:233], v[198:199], v[154:155], v[232:233]
	v_pk_mul_f32 v[140:141], v[60:61], v[136:137] op_sel_hi:[1,0]
	v_pk_mul_f32 v[234:235], v[234:235], s[96:97] op_sel_hi:[1,0]
	v_pk_fma_f32 v[234:235], v[192:193], v[140:141], v[234:235]
	v_pk_mul_f32 v[154:155], v[62:63], v[136:137] op_sel_hi:[1,0]
	v_pk_mul_f32 v[236:237], v[236:237], s[96:97] op_sel_hi:[1,0]
	v_pk_fma_f32 v[236:237], v[190:191], v[154:155], v[236:237]
	v_cvt_pk_bf16_f32 v238, v230, v231
	v_cvt_pk_bf16_f32 v239, v232, v233
	v_cvt_pk_bf16_f32 v240, v234, v235
	v_cvt_pk_bf16_f32 v241, v236, v237
	global_store_dwordx4 v[204:205], v[238:241], off
	v_lshlrev_b32_e32 v230, 16, v146
	v_and_b32_e32 v231, 0xffff0000, v146
	v_lshlrev_b32_e32 v232, 16, v147
	v_and_b32_e32 v233, 0xffff0000, v147
	v_lshlrev_b32_e32 v234, 16, v148
	v_and_b32_e32 v235, 0xffff0000, v148
	v_lshlrev_b32_e32 v236, 16, v149
	v_and_b32_e32 v237, 0xffff0000, v149
	v_pk_mul_f32 v[140:141], v[56:57], v[136:137] op_sel_hi:[1,0]
	v_pk_mul_f32 v[230:231], v[230:231], s[96:97] op_sel_hi:[1,0]
	v_pk_fma_f32 v[230:231], v[196:197], v[140:141], v[230:231]
	v_pk_mul_f32 v[154:155], v[58:59], v[136:137] op_sel_hi:[1,0]
	v_pk_mul_f32 v[232:233], v[232:233], s[96:97] op_sel_hi:[1,0]
	v_pk_fma_f32 v[232:233], v[194:195], v[154:155], v[232:233]
	v_pk_mul_f32 v[140:141], v[52:53], v[136:137] op_sel_hi:[1,0]
	v_pk_mul_f32 v[234:235], v[234:235], s[96:97] op_sel_hi:[1,0]
	v_pk_fma_f32 v[234:235], v[188:189], v[140:141], v[234:235]
	v_pk_mul_f32 v[154:155], v[54:55], v[136:137] op_sel_hi:[1,0]
	v_pk_mul_f32 v[236:237], v[236:237], s[96:97] op_sel_hi:[1,0]
	v_pk_fma_f32 v[236:237], v[186:187], v[154:155], v[236:237]
	v_cvt_pk_bf16_f32 v242, v230, v231
	v_cvt_pk_bf16_f32 v243, v232, v233
	v_cvt_pk_bf16_f32 v244, v234, v235
	v_cvt_pk_bf16_f32 v245, v236, v237
	global_store_dwordx4 v[204:205], v[242:245], off offset:256
	v_lshl_add_u64 v[204:205], v[204:205], 0, s[36:37]
	v_lshl_add_u64 v[202:203], v[202:203], 0, s[36:37]
	global_load_dwordx4 v[142:145], v[202:203], off
	global_load_dwordx4 v[146:149], v[202:203], off offset:256
	s_waitcnt vmcnt(4)
	v_lshlrev_b32_e32 v230, 16, v150
	v_and_b32_e32 v231, 0xffff0000, v150
	v_lshlrev_b32_e32 v232, 16, v151
	v_and_b32_e32 v233, 0xffff0000, v151
	v_lshlrev_b32_e32 v234, 16, v152
	v_and_b32_e32 v235, 0xffff0000, v152
	v_lshlrev_b32_e32 v236, 16, v153
	v_and_b32_e32 v237, 0xffff0000, v153
	v_pk_mul_f32 v[140:141], v[48:49], v[136:137] op_sel:[0,1]
	v_pk_mul_f32 v[230:231], v[230:231], s[96:97] op_sel_hi:[1,0]
	v_pk_fma_f32 v[230:231], v[200:201], v[140:141], v[230:231]
	v_pk_mul_f32 v[154:155], v[50:51], v[136:137] op_sel:[0,1]
	v_pk_mul_f32 v[232:233], v[232:233], s[96:97] op_sel_hi:[1,0]
	v_pk_fma_f32 v[232:233], v[198:199], v[154:155], v[232:233]
	v_pk_mul_f32 v[140:141], v[44:45], v[136:137] op_sel:[0,1]
	v_pk_mul_f32 v[234:235], v[234:235], s[96:97] op_sel_hi:[1,0]
	v_pk_fma_f32 v[234:235], v[192:193], v[140:141], v[234:235]
	v_pk_mul_f32 v[154:155], v[46:47], v[136:137] op_sel:[0,1]
	v_pk_mul_f32 v[236:237], v[236:237], s[96:97] op_sel_hi:[1,0]
	v_pk_fma_f32 v[236:237], v[190:191], v[154:155], v[236:237]
	v_cvt_pk_bf16_f32 v238, v230, v231
	v_cvt_pk_bf16_f32 v239, v232, v233
	v_cvt_pk_bf16_f32 v240, v234, v235
	v_cvt_pk_bf16_f32 v241, v236, v237
	global_store_dwordx4 v[204:205], v[238:241], off
	v_lshlrev_b32_e32 v230, 16, v210
	v_and_b32_e32 v231, 0xffff0000, v210
	v_lshlrev_b32_e32 v232, 16, v211
	v_and_b32_e32 v233, 0xffff0000, v211
	v_lshlrev_b32_e32 v234, 16, v212
	v_and_b32_e32 v235, 0xffff0000, v212
	v_lshlrev_b32_e32 v236, 16, v213
	v_and_b32_e32 v237, 0xffff0000, v213
	v_pk_mul_f32 v[140:141], v[40:41], v[136:137] op_sel:[0,1]
	v_pk_mul_f32 v[230:231], v[230:231], s[96:97] op_sel_hi:[1,0]
	v_pk_fma_f32 v[230:231], v[196:197], v[140:141], v[230:231]
	v_pk_mul_f32 v[154:155], v[42:43], v[136:137] op_sel:[0,1]
	v_pk_mul_f32 v[232:233], v[232:233], s[96:97] op_sel_hi:[1,0]
	v_pk_fma_f32 v[232:233], v[194:195], v[154:155], v[232:233]
	v_pk_mul_f32 v[140:141], v[36:37], v[136:137] op_sel:[0,1]
	v_pk_mul_f32 v[234:235], v[234:235], s[96:97] op_sel_hi:[1,0]
	v_pk_fma_f32 v[234:235], v[188:189], v[140:141], v[234:235]
	v_pk_mul_f32 v[154:155], v[38:39], v[136:137] op_sel:[0,1]
	v_pk_mul_f32 v[236:237], v[236:237], s[96:97] op_sel_hi:[1,0]
	v_pk_fma_f32 v[236:237], v[186:187], v[154:155], v[236:237]
	v_cvt_pk_bf16_f32 v242, v230, v231
	v_cvt_pk_bf16_f32 v243, v232, v233
	v_cvt_pk_bf16_f32 v244, v234, v235
	v_cvt_pk_bf16_f32 v245, v236, v237
	global_store_dwordx4 v[204:205], v[242:245], off offset:256
	v_lshl_add_u64 v[204:205], v[204:205], 0, s[36:37]
	v_lshl_add_u64 v[202:203], v[202:203], 0, s[36:37]
	global_load_dwordx4 v[150:153], v[202:203], off
	global_load_dwordx4 v[210:213], v[202:203], off offset:256
	s_waitcnt vmcnt(4)
; #define GAS __attribute__((address_space(1)))
; __device__ __forceinline__ unsigned cvt_pk_bf16(float lo, float hi) { const f32x2 v = {lo, hi}; const bf16x2_t b = __builtin_convertvector(v, bf16x2_t); return __builtin_bit_cast(unsigned, b); }
;     template <bool XF32> __device__ __forceinline__ void store_res(const f32x4 (&acc)[2][2][4][2], const pg8::Unit& u, int wr, int wc, int fr, int fq) const {
;     ...
;             for (int m = 0; m < 4; ++m) { const size_t off = (size_t)(row0 + ai * 128 + m * 16) * DM + col0;
; #pragma unroll
;                 for (int bj = 0; bj < 2; ++bj) { f32x4 x0, x1;
;                     if (XF32) { x0 = *(const GAS f32x4*)(xin + off + bj * 128); x1 = *(const GAS f32x4*)(xin + off + bj * 128 + 4); }
;                     else { const u32x4 xb = xpre[m][bj];
;                         x0 = (f32x4){bf2f((unsigned short)(xb.x & 0xffff)), bf2f((unsigned short)(xb.x >> 16)), bf2f((unsigned short)(xb.y & 0xffff)), bf2f((unsigned short)(xb.y >> 16))};
;                         x1 = (f32x4){bf2f((unsigned short)(xb.z & 0xffff)), bf2f((unsigned short)(xb.z >> 16)), bf2f((unsigned short)(xb.w & 0xffff)), bf2f((unsigned short)(xb.w >> 16))}; }
;                     const f32x4 z0 = ALPHA * x0 + gv[bj][0] * (acc[ai][bj][m][0] * rsc[m]), z1 = ALPHA * x1 + gv[bj][1] * (acc[ai][bj][m][1] * rsc[m]);
;                     u32x4 w; w.x = cvt_pk_bf16(z0[0], z0[1]); w.y = cvt_pk_bf16(z0[2], z0[3]); w.z = cvt_pk_bf16(z1[0], z1[1]); w.w = cvt_pk_bf16(z1[2], z1[3]);
;                     *(GAS u32x4*)(O + off + bj * 128) = w; }
	v_lshlrev_b32_e32 v230, 16, v142
	v_and_b32_e32 v231, 0xffff0000, v142
	v_lshlrev_b32_e32 v232, 16, v143
	v_and_b32_e32 v233, 0xffff0000, v143
	v_lshlrev_b32_e32 v234, 16, v144
	v_and_b32_e32 v235, 0xffff0000, v144
	v_lshlrev_b32_e32 v236, 16, v145
	v_and_b32_e32 v237, 0xffff0000, v145
	v_pk_mul_f32 v[140:141], v[32:33], v[138:139] op_sel_hi:[1,0]
	v_pk_mul_f32 v[230:231], v[230:231], s[96:97] op_sel_hi:[1,0]
	v_pk_fma_f32 v[230:231], v[200:201], v[140:141], v[230:231]
	v_pk_mul_f32 v[154:155], v[34:35], v[138:139] op_sel_hi:[1,0]
	v_pk_mul_f32 v[232:233], v[232:233], s[96:97] op_sel_hi:[1,0]
	v_pk_fma_f32 v[232:233], v[198:199], v[154:155], v[232:233]
	v_pk_mul_f32 v[140:141], v[28:29], v[138:139] op_sel_hi:[1,0]
	v_pk_mul_f32 v[234:235], v[234:235], s[96:97] op_sel_hi:[1,0]
	v_pk_fma_f32 v[234:235], v[192:193], v[140:141], v[234:235]
	v_pk_mul_f32 v[154:155], v[30:31], v[138:139] op_sel_hi:[1,0]
	v_pk_mul_f32 v[236:237], v[236:237], s[96:97] op_sel_hi:[1,0]
	v_pk_fma_f32 v[236:237], v[190:191], v[154:155], v[236:237]
	v_cvt_pk_bf16_f32 v238, v230, v231
	v_cvt_pk_bf16_f32 v239, v232, v233
	v_cvt_pk_bf16_f32 v240, v234, v235
	v_cvt_pk_bf16_f32 v241, v236, v237
	global_store_dwordx4 v[204:205], v[238:241], off
	v_lshlrev_b32_e32 v230, 16, v146
	v_and_b32_e32 v231, 0xffff0000, v146
	v_lshlrev_b32_e32 v232, 16, v147
	v_and_b32_e32 v233, 0xffff0000, v147
	v_lshlrev_b32_e32 v234, 16, v148
	v_and_b32_e32 v235, 0xffff0000, v148
	v_lshlrev_b32_e32 v236, 16, v149
	v_and_b32_e32 v237, 0xffff0000, v149
	v_pk_mul_f32 v[140:141], v[24:25], v[138:139] op_sel_hi:[1,0]
	v_pk_mul_f32 v[230:231], v[230:231], s[96:97] op_sel_hi:[1,0]
	v_pk_fma_f32 v[230:231], v[196:197], v[140:141], v[230:231]
	v_pk_mul_f32 v[154:155], v[26:27], v[138:139] op_sel_hi:[1,0]
	v_pk_mul_f32 v[232:233], v[232:233], s[96:97] op_sel_hi:[1,0]
	v_pk_fma_f32 v[232:233], v[194:195], v[154:155], v[232:233]
	v_pk_mul_f32 v[140:141], v[20:21], v[138:139] op_sel_hi:[1,0]
	v_pk_mul_f32 v[234:235], v[234:235], s[96:97] op_sel_hi:[1,0]
	v_pk_fma_f32 v[234:235], v[188:189], v[140:141], v[234:235]
	v_pk_mul_f32 v[154:155], v[22:23], v[138:139] op_sel_hi:[1,0]
	v_pk_mul_f32 v[236:237], v[236:237], s[96:97] op_sel_hi:[1,0]
	v_pk_fma_f32 v[236:237], v[186:187], v[154:155], v[236:237]
	v_cvt_pk_bf16_f32 v242, v230, v231
	v_cvt_pk_bf16_f32 v243, v232, v233
	v_cvt_pk_bf16_f32 v244, v234, v235
	v_cvt_pk_bf16_f32 v245, v236, v237
	global_store_dwordx4 v[204:205], v[242:245], off offset:256
	v_lshl_add_u64 v[204:205], v[204:205], 0, s[36:37]
	s_waitcnt vmcnt(2)
	v_lshlrev_b32_e32 v230, 16, v150
	v_and_b32_e32 v231, 0xffff0000, v150
	v_lshlrev_b32_e32 v232, 16, v151
	v_and_b32_e32 v233, 0xffff0000, v151
	v_lshlrev_b32_e32 v234, 16, v152
	v_and_b32_e32 v235, 0xffff0000, v152
	v_lshlrev_b32_e32 v236, 16, v153
	v_and_b32_e32 v237, 0xffff0000, v153
	v_pk_mul_f32 v[140:141], v[16:17], v[138:139] op_sel:[0,1]
	v_pk_mul_f32 v[230:231], v[230:231], s[96:97] op_sel_hi:[1,0]
	v_pk_fma_f32 v[230:231], v[200:201], v[140:141], v[230:231]
	v_pk_mul_f32 v[154:155], v[18:19], v[138:139] op_sel:[0,1]
	v_pk_mul_f32 v[232:233], v[232:233], s[96:97] op_sel_hi:[1,0]
	v_pk_fma_f32 v[232:233], v[198:199], v[154:155], v[232:233]
	v_pk_mul_f32 v[140:141], v[12:13], v[138:139] op_sel:[0,1]
	v_pk_mul_f32 v[234:235], v[234:235], s[96:97] op_sel_hi:[1,0]
	v_pk_fma_f32 v[234:235], v[192:193], v[140:141], v[234:235]
	v_pk_mul_f32 v[154:155], v[14:15], v[138:139] op_sel:[0,1]
	v_pk_mul_f32 v[236:237], v[236:237], s[96:97] op_sel_hi:[1,0]
	v_pk_fma_f32 v[236:237], v[190:191], v[154:155], v[236:237]
	v_cvt_pk_bf16_f32 v238, v230, v231
	v_cvt_pk_bf16_f32 v239, v232, v233
	v_cvt_pk_bf16_f32 v240, v234, v235
	v_cvt_pk_bf16_f32 v241, v236, v237
	global_store_dwordx4 v[204:205], v[238:241], off
	v_lshlrev_b32_e32 v230, 16, v210
	v_and_b32_e32 v231, 0xffff0000, v210
	v_lshlrev_b32_e32 v232, 16, v211
	v_and_b32_e32 v233, 0xffff0000, v211
	v_lshlrev_b32_e32 v234, 16, v212
	v_and_b32_e32 v235, 0xffff0000, v212
	v_lshlrev_b32_e32 v236, 16, v213
	v_and_b32_e32 v237, 0xffff0000, v213
	v_pk_mul_f32 v[140:141], v[8:9], v[138:139] op_sel:[0,1]
	v_pk_mul_f32 v[230:231], v[230:231], s[96:97] op_sel_hi:[1,0]
	v_pk_fma_f32 v[230:231], v[196:197], v[140:141], v[230:231]
	v_pk_mul_f32 v[154:155], v[10:11], v[138:139] op_sel:[0,1]
	v_pk_mul_f32 v[232:233], v[232:233], s[96:97] op_sel_hi:[1,0]
	v_pk_fma_f32 v[232:233], v[194:195], v[154:155], v[232:233]
	v_pk_mul_f32 v[140:141], v[4:5], v[138:139] op_sel:[0,1]
	v_pk_mul_f32 v[234:235], v[234:235], s[96:97] op_sel_hi:[1,0]
	v_pk_fma_f32 v[234:235], v[188:189], v[140:141], v[234:235]
	v_pk_mul_f32 v[154:155], v[6:7], v[138:139] op_sel:[0,1]
	v_pk_mul_f32 v[236:237], v[236:237], s[96:97] op_sel_hi:[1,0]
	v_pk_fma_f32 v[236:237], v[186:187], v[154:155], v[236:237]
	v_cvt_pk_bf16_f32 v242, v230, v231
	v_cvt_pk_bf16_f32 v243, v232, v233
	v_cvt_pk_bf16_f32 v244, v234, v235
	v_cvt_pk_bf16_f32 v245, v236, v237
	global_store_dwordx4 v[204:205], v[242:245], off offset:256
	s_branch .LBB0_413
